# P0 rmsnorm rows: gain vectors loaded up front instead of one per store (was store->load->vmcnt(0) x8 per row)
# speedup vs baseline: 1.0074x; 1.0009x over previous
; #define GAS __attribute__((address_space(1)))
; __device__ __forceinline__ unsigned pk2(float lo, float hi) { return f2bf(lo) | (f2bf(hi) << 16); }
; __device__ __forceinline__ float wave_sum(float v) { v += shx<1>(v); v += shx<2>(v); v += shx<4>(v); v += shx<8>(v); v += shx<16>(v); return sum32(v); }
; __device__ __forceinline__ void rms_row_to_bf16(const float* xrow, const float* g, bf16* orow, int lane) {
;     const GAS f32x4* xr = (const GAS f32x4*)xrow + lane; const GAS f32x4* gr = (const GAS f32x4*)g + lane;
;     f32x4 v[8]; float s = 0.f;
; #pragma unroll
;     for (int j = 0; j < 8; ++j) { v[j] = __builtin_nontemporal_load(xr + 64 * j); s += (v[j].x * v[j].x + v[j].y * v[j].y) + (v[j].z * v[j].z + v[j].w * v[j].w); }
;     const float rstd = 1.0f / sqrtf(wave_sum(s) * (1.f / DM) + EPS);
;     GAS unsigned long long* o8 = (GAS unsigned long long*)orow + lane;
; #pragma unroll
;     for (int j = 0; j < 8; ++j) { const f32x4 gg = gr[64 * j]; o8[64 * j] = (unsigned long long)pk2(v[j].x * rstd * gg.x, v[j].y * rstd * gg.y) | ((unsigned long long)pk2(v[j].z * rstd * gg.z, v[j].w * rstd * gg.w) << 32); }
; }
; __device__ __forceinline__ void p0_prologue(const Args& a, LAS unsigned char* lds, int wave, int lane, int G) {
;     ...
;     for (int m = gw; m < M + MMEM; m += NGW) {
;         if (m < M) rms_row_to_bf16(a.in[I_X] + (size_t)m * DM, a.in[I_GMIX], (bf16*)(ws + WS_XN) + (size_t)m * DM, lane);
;         else rms_row_to_bf16(a.in[I_MEM] + (size_t)(m - M) * DM, a.in[I_GMEM], (bf16*)(ws + WS_MN) + (size_t)(m - M) * DM, lane);
.LBB0_108:
	s_cmpk_gt_i32 s6, 0x1fff
	s_mov_b64 s[0:1], -1
	s_cbranch_scc0 .LBB0_110
	s_add_i32 s20, s6, 0xffffe000
	s_lshl_b64 s[0:1], s[20:21], 12
	s_add_u32 s22, s81, s0
	s_addc_u32 s23, s88, s1
	s_lshl_b64 s[0:1], s[20:21], 13
	v_lshl_add_u64 v[2:3], v[56:57], 0, s[0:1]
	global_load_dwordx4 v[62:65], v[2:3], off nt
	global_load_dwordx4 v[66:69], v[2:3], off offset:1024 nt
	global_load_dwordx4 v[22:25], v[2:3], off offset:2048 nt
	global_load_dwordx4 v[18:21], v[2:3], off offset:3072 nt
	v_add_co_u32_e32 v2, vcc, s5, v2
	s_waitcnt vmcnt(3)
	v_mul_f32_e32 v26, v63, v63
	v_addc_co_u32_e32 v3, vcc, 0, v3, vcc
	global_load_dwordx4 v[14:17], v[2:3], off nt
	global_load_dwordx4 v[10:13], v[2:3], off offset:1024 nt
	global_load_dwordx4 v[6:9], v[2:3], off offset:2048 nt
	s_nop 0
	global_load_dwordx4 v[2:5], v[2:3], off offset:3072 nt
	s_nop 0
	global_load_dwordx4 v[70:73], v[30:31], off
	v_mul_f32_e32 v27, v65, v65
	s_waitcnt vmcnt(7)
	v_mul_f32_e32 v28, v67, v67
	v_mul_f32_e32 v29, v69, v69
	s_waitcnt vmcnt(6)
	v_mul_f32_e32 v40, v23, v23
	v_mul_f32_e32 v41, v25, v25
	v_fmac_f32_e32 v26, v62, v62
	v_fmac_f32_e32 v27, v64, v64
	v_fmac_f32_e32 v28, v66, v66
	v_fmac_f32_e32 v29, v68, v68
	s_waitcnt vmcnt(5)
	v_mul_f32_e32 v74, v19, v19
	v_mul_f32_e32 v75, v21, v21
	v_fmac_f32_e32 v40, v22, v22
	v_fmac_f32_e32 v41, v24, v24
	v_add_f32_e32 v26, v26, v27
	v_add_f32_e32 v27, v28, v29
	v_fmac_f32_e32 v74, v18, v18
	v_fmac_f32_e32 v75, v20, v20
	v_add_f32_e32 v28, v40, v41
	v_add_f32_e32 v26, v26, v27
	v_add_f32_e32 v29, v74, v75
	v_add_f32_e32 v26, v26, v28
	v_add_f32_e32 v26, v26, v29
	s_waitcnt vmcnt(4)
	v_mul_f32_e32 v76, v15, v15
	v_mul_f32_e32 v77, v17, v17
	s_waitcnt vmcnt(3)
	v_mul_f32_e32 v78, v11, v11
	v_mul_f32_e32 v79, v13, v13
	v_fmac_f32_e32 v76, v14, v14
	v_fmac_f32_e32 v77, v16, v16
	s_waitcnt vmcnt(2)
	v_mul_f32_e32 v80, v7, v7
	v_mul_f32_e32 v81, v9, v9
	v_fmac_f32_e32 v78, v10, v10
	v_fmac_f32_e32 v79, v12, v12
	v_add_f32_e32 v27, v76, v77
	s_waitcnt vmcnt(1)
	global_load_dwordx4 v[96:99], v[30:31], off offset:1024
	global_load_dwordx4 v[100:103], v[30:31], off offset:2048
	global_load_dwordx4 v[104:107], v[30:31], off offset:3072
	global_load_dwordx4 v[108:111], v[32:33], off
	global_load_dwordx4 v[112:115], v[34:35], off
	global_load_dwordx4 v[116:119], v[36:37], off
	global_load_dwordx4 v[120:123], v[42:43], off
	v_mul_f32_e32 v82, v3, v3
	v_mul_f32_e32 v83, v5, v5
	v_fmac_f32_e32 v80, v6, v6
	v_fmac_f32_e32 v81, v8, v8
	v_add_f32_e32 v40, v78, v79
	v_add_f32_e32 v26, v26, v27
	v_fmac_f32_e32 v82, v2, v2
	v_fmac_f32_e32 v83, v4, v4
	v_add_f32_e32 v41, v80, v81
	v_add_f32_e32 v26, v26, v40
	v_add_f32_e32 v74, v82, v83
	v_add_f32_e32 v26, v26, v41
	v_add_f32_e32 v26, v26, v74
	s_nop 1
	v_mov_b32_dpp v27, v26 quad_perm:[1,0,3,2] row_mask:0xf bank_mask:0xf
	s_waitcnt lgkmcnt(0)
	v_add_f32_e32 v26, v26, v27
	s_nop 1
	v_mov_b32_dpp v27, v26 quad_perm:[2,3,0,1] row_mask:0xf bank_mask:0xf
	s_waitcnt lgkmcnt(0)
	v_add_f32_e32 v26, v26, v27
	s_nop 1
	v_mov_b32_dpp v27, v26 quad_perm:[3,2,1,0] row_mask:0xf bank_mask:0xf
	s_nop 1
	v_mov_b32_dpp v27, v27 row_half_mirror row_mask:0xf bank_mask:0xf
	s_waitcnt lgkmcnt(0)
	v_add_f32_e32 v26, v26, v27
	s_nop 1
	v_mov_b32_dpp v27, v26 row_half_mirror row_mask:0xf bank_mask:0xf
	s_nop 1
	v_mov_b32_dpp v27, v27 row_mirror row_mask:0xf bank_mask:0xf
	s_waitcnt lgkmcnt(0)
	v_add_f32_e32 v26, v26, v27
	ds_swizzle_b32 v27, v26 offset:swizzle(SWAP,16)
	s_waitcnt lgkmcnt(0)
	v_add_f32_e32 v26, v26, v27
	v_mov_b32_e32 v27, v26
	s_nop 1
	v_permlane32_swap_b32_e32 v26, v27
	v_add_f32_e32 v26, v26, v27
	v_fmamk_f32 v26, v26, 0x3a000000, v44
	v_mul_f32_e32 v27, 0x4f800000, v26
	v_cmp_gt_f32_e32 vcc, s7, v26
	s_nop 1
	v_cndmask_b32_e32 v26, v26, v27, vcc
	v_sqrt_f32_e32 v27, v26
	s_nop 0
	v_add_u32_e32 v28, -1, v27
	v_add_u32_e32 v29, 1, v27
	v_fma_f32 v40, -v28, v27, v26
	v_fma_f32 v41, -v29, v27, v26
	v_cmp_ge_f32_e64 s[0:1], 0, v40
	s_nop 1
	v_cndmask_b32_e64 v27, v27, v28, s[0:1]
	v_cmp_lt_f32_e64 s[0:1], 0, v41
	s_nop 1
	v_cndmask_b32_e64 v27, v27, v29, s[0:1]
	v_mul_f32_e32 v28, 0x37800000, v27
	v_cndmask_b32_e32 v27, v27, v28, vcc
	v_cmp_class_f32_e32 vcc, v26, v45
	s_nop 1
	v_cndmask_b32_e32 v26, v27, v26, vcc
	v_div_scale_f32 v27, s[0:1], v26, v26, 1.0
	v_rcp_f32_e32 v28, v27
	v_div_scale_f32 v29, vcc, 1.0, v26, 1.0
	s_mov_b64 s[0:1], 0
	v_fma_f32 v40, -v27, v28, 1.0
	v_fmac_f32_e32 v28, v40, v28
	v_mul_f32_e32 v40, v29, v28
	v_fma_f32 v41, -v27, v40, v29
	v_fmac_f32_e32 v40, v41, v28
	v_fma_f32 v27, -v27, v40, v29
	v_div_fmas_f32 v27, v27, v28, v40
	v_div_fixup_f32 v26, v27, v26, 1.0
	v_mul_f32_e32 v27, v62, v26
	v_mul_f32_e32 v29, v64, v26
	v_mul_f32_e32 v28, v63, v26
	v_mul_f32_e32 v40, v65, v26
	s_waitcnt vmcnt(0)
; #define GAS __attribute__((address_space(1)))
; __device__ __forceinline__ unsigned pk2(float lo, float hi) { return f2bf(lo) | (f2bf(hi) << 16); }
; __device__ __forceinline__ void rms_row_to_bf16(const float* xrow, const float* g, bf16* orow, int lane) {
;     ...
;     GAS unsigned long long* o8 = (GAS unsigned long long*)orow + lane;
; #pragma unroll
;     for (int j = 0; j < 8; ++j) { const f32x4 gg = gr[64 * j]; o8[64 * j] = (unsigned long long)pk2(v[j].x * rstd * gg.x, v[j].y * rstd * gg.y) | ((unsigned long long)pk2(v[j].z * rstd * gg.z, v[j].w * rstd * gg.w) << 32); }
	v_mul_f32_e32 v27, v70, v27
	v_mul_f32_e32 v29, v72, v29
	v_mul_f32_e32 v28, v71, v28
	v_mul_f32_e32 v40, v73, v40
	v_bfe_u32 v41, v27, 16, 1
	v_bfe_u32 v63, v29, 16, 1
	v_bfe_u32 v62, v28, 16, 1
	v_bfe_u32 v64, v40, 16, 1
	v_add3_u32 v27, v27, v41, s26
	v_add3_u32 v29, v29, v63, s26
	v_add3_u32 v28, v28, v62, s26
	v_add3_u32 v40, v40, v64, s26
	v_lshrrev_b32_e32 v27, 16, v27
	v_lshrrev_b32_e32 v29, 16, v29
	v_and_or_b32 v28, v28, s27, v27
	v_and_or_b32 v29, v40, s27, v29
	global_store_dwordx2 v60, v[28:29], s[22:23]
	v_mul_f32_e32 v27, v66, v26
	v_mul_f32_e32 v29, v68, v26
	v_mul_f32_e32 v28, v67, v26
	v_mul_f32_e32 v40, v69, v26
	v_mul_f32_e32 v22, v22, v26
	v_mul_f32_e32 v24, v24, v26
	v_mul_f32_e32 v23, v23, v26
	v_mul_f32_e32 v25, v25, v26
	v_mul_f32_e32 v18, v18, v26
	v_mul_f32_e32 v20, v20, v26
	v_mul_f32_e32 v19, v19, v26
	v_mul_f32_e32 v21, v21, v26
	v_mul_f32_e32 v14, v14, v26
	v_mul_f32_e32 v16, v16, v26
	v_mul_f32_e32 v15, v15, v26
	v_mul_f32_e32 v17, v17, v26
	v_mul_f32_e32 v10, v10, v26
	v_mul_f32_e32 v12, v12, v26
	v_mul_f32_e32 v11, v11, v26
	v_mul_f32_e32 v13, v13, v26
	v_mul_f32_e32 v6, v6, v26
	v_mul_f32_e32 v8, v8, v26
	v_mul_f32_e32 v7, v7, v26
	v_mul_f32_e32 v9, v9, v26
	v_mov_b32_e32 v62, v96
	v_mov_b32_e32 v63, v97
	v_mov_b32_e32 v64, v98
	v_mov_b32_e32 v65, v99
	v_mul_f32_e32 v27, v62, v27
	v_mul_f32_e32 v29, v64, v29
	v_mul_f32_e32 v28, v63, v28
	v_mul_f32_e32 v40, v65, v40
	v_bfe_u32 v41, v27, 16, 1
	v_bfe_u32 v63, v29, 16, 1
	v_bfe_u32 v62, v28, 16, 1
	v_bfe_u32 v64, v40, 16, 1
	v_add3_u32 v27, v27, v41, s26
	v_add3_u32 v29, v29, v63, s26
	v_add3_u32 v28, v28, v62, s26
	v_add3_u32 v40, v40, v64, s26
	v_lshrrev_b32_e32 v27, 16, v27
	v_lshrrev_b32_e32 v29, 16, v29
	v_and_or_b32 v28, v28, s27, v27
	v_and_or_b32 v29, v40, s27, v29
	global_store_dwordx2 v60, v[28:29], s[22:23] offset:512
	v_mov_b32_e32 v62, v100
	v_mov_b32_e32 v63, v101
	v_mov_b32_e32 v64, v102
	v_mov_b32_e32 v65, v103
	v_mul_f32_e32 v22, v62, v22
	v_mul_f32_e32 v24, v64, v24
	v_mul_f32_e32 v23, v63, v23
	v_mul_f32_e32 v25, v65, v25
	v_bfe_u32 v27, v22, 16, 1
	v_bfe_u32 v29, v24, 16, 1
	v_bfe_u32 v28, v23, 16, 1
	v_bfe_u32 v40, v25, 16, 1
	v_add3_u32 v22, v22, v27, s26
	v_add3_u32 v24, v24, v29, s26
	v_add3_u32 v23, v23, v28, s26
	v_add3_u32 v25, v25, v40, s26
	v_lshrrev_b32_e32 v22, 16, v22
	v_lshrrev_b32_e32 v24, 16, v24
	v_and_or_b32 v22, v23, s27, v22
	v_and_or_b32 v23, v25, s27, v24
	global_store_dwordx2 v60, v[22:23], s[22:23] offset:1024
	v_pk_mul_f32 v[2:3], v[2:3], v[26:27] op_sel_hi:[1,0]
	v_mul_f32_e32 v27, v4, v26
	v_mov_b32_e32 v22, v104
	v_mov_b32_e32 v23, v105
	v_mov_b32_e32 v24, v106
	v_mov_b32_e32 v25, v107
	v_mul_f32_e32 v18, v18, v22
	v_mul_f32_e32 v20, v20, v24
	v_mul_f32_e32 v19, v19, v23
	v_mul_f32_e32 v21, v21, v25
	v_bfe_u32 v22, v18, 16, 1
	v_bfe_u32 v24, v20, 16, 1
	v_bfe_u32 v23, v19, 16, 1
	v_bfe_u32 v25, v21, 16, 1
	v_add3_u32 v18, v18, v22, s26
	v_add3_u32 v20, v20, v24, s26
	v_add3_u32 v19, v19, v23, s26
	v_add3_u32 v21, v21, v25, s26
	v_lshrrev_b32_e32 v18, 16, v18
	v_lshrrev_b32_e32 v20, 16, v20
	v_and_or_b32 v18, v19, s27, v18
	v_and_or_b32 v19, v21, s27, v20
	global_store_dwordx2 v60, v[18:19], s[22:23] offset:1536
	v_mov_b32_e32 v18, v108
	v_mov_b32_e32 v19, v109
	v_mov_b32_e32 v20, v110
	v_mov_b32_e32 v21, v111
	v_mul_f32_e32 v14, v14, v18
	v_mul_f32_e32 v16, v16, v20
	v_mul_f32_e32 v15, v15, v19
	v_mul_f32_e32 v17, v17, v21
	v_bfe_u32 v18, v14, 16, 1
	v_bfe_u32 v20, v16, 16, 1
	v_bfe_u32 v19, v15, 16, 1
	v_bfe_u32 v21, v17, 16, 1
	v_add3_u32 v14, v14, v18, s26
	v_add3_u32 v16, v16, v20, s26
	v_add3_u32 v15, v15, v19, s26
	v_add3_u32 v17, v17, v21, s26
	v_lshrrev_b32_e32 v14, 16, v14
	v_lshrrev_b32_e32 v16, 16, v16
	v_and_or_b32 v14, v15, s27, v14
	v_and_or_b32 v15, v17, s27, v16
	global_store_dwordx2 v60, v[14:15], s[22:23] offset:2048
	v_mov_b32_e32 v14, v112
	v_mov_b32_e32 v15, v113
	v_mov_b32_e32 v16, v114
	v_mov_b32_e32 v17, v115
	v_mul_f32_e32 v10, v10, v14
	v_mul_f32_e32 v12, v12, v16
	v_mul_f32_e32 v11, v11, v15
	v_mul_f32_e32 v13, v13, v17
	v_bfe_u32 v14, v10, 16, 1
	v_bfe_u32 v16, v12, 16, 1
	v_bfe_u32 v15, v11, 16, 1
	v_bfe_u32 v17, v13, 16, 1
	v_add3_u32 v10, v10, v14, s26
	v_add3_u32 v12, v12, v16, s26
	v_add3_u32 v11, v11, v15, s26
	v_add3_u32 v13, v13, v17, s26
	v_lshrrev_b32_e32 v10, 16, v10
	v_lshrrev_b32_e32 v12, 16, v12
	v_and_or_b32 v10, v11, s27, v10
	v_and_or_b32 v11, v13, s27, v12
	global_store_dwordx2 v60, v[10:11], s[22:23] offset:2560
	v_mov_b32_e32 v10, v116
	v_mov_b32_e32 v11, v117
	v_mov_b32_e32 v12, v118
	v_mov_b32_e32 v13, v119
	v_mul_f32_e32 v6, v6, v10
	v_mul_f32_e32 v8, v8, v12
	v_mul_f32_e32 v7, v7, v11
	v_mul_f32_e32 v9, v9, v13
	v_bfe_u32 v10, v6, 16, 1
	v_bfe_u32 v12, v8, 16, 1
	v_bfe_u32 v11, v7, 16, 1
	v_bfe_u32 v13, v9, 16, 1
	v_add3_u32 v6, v6, v10, s26
	v_add3_u32 v8, v8, v12, s26
	v_add3_u32 v7, v7, v11, s26
	v_add3_u32 v9, v9, v13, s26
	v_lshrrev_b32_e32 v6, 16, v6
	v_lshrrev_b32_e32 v8, 16, v8
	v_and_or_b32 v6, v7, s27, v6
	v_and_or_b32 v7, v9, s27, v8
	global_store_dwordx2 v60, v[6:7], s[22:23] offset:3072
	v_mov_b32_e32 v6, v120
	v_mov_b32_e32 v7, v121
	v_mov_b32_e32 v8, v122
	v_mov_b32_e32 v9, v123
	v_pk_mul_f32 v[2:3], v[2:3], v[6:7]
	s_nop 0
	v_and_b32_sdwa v7, v2, v61 dst_sel:DWORD dst_unused:UNUSED_PAD src0_sel:WORD_1 src1_sel:DWORD
	v_and_b32_sdwa v6, v3, v61 dst_sel:DWORD dst_unused:UNUSED_PAD src0_sel:WORD_1 src1_sel:DWORD
	v_add3_u32 v2, v2, v7, s26
	v_pk_mov_b32 v[4:5], v[4:5], v[8:9] op_sel:[1,0]
	v_add3_u32 v3, v3, v6, s26
	v_lshrrev_b32_e32 v2, 16, v2
	v_pk_mul_f32 v[4:5], v[4:5], v[26:27]
	v_and_or_b32 v2, v3, s27, v2
; #define GAS __attribute__((address_space(1)))
; __device__ __forceinline__ unsigned pk2(float lo, float hi) { return f2bf(lo) | (f2bf(hi) << 16); }
; __device__ __forceinline__ float wave_sum(float v) { v += shx<1>(v); v += shx<2>(v); v += shx<4>(v); v += shx<8>(v); v += shx<16>(v); return sum32(v); }
; __device__ __forceinline__ void rms_row_to_bf16(const float* xrow, const float* g, bf16* orow, int lane) {
;     const GAS f32x4* xr = (const GAS f32x4*)xrow + lane; const GAS f32x4* gr = (const GAS f32x4*)g + lane;
;     f32x4 v[8]; float s = 0.f;
; #pragma unroll
;     for (int j = 0; j < 8; ++j) { v[j] = __builtin_nontemporal_load(xr + 64 * j); s += (v[j].x * v[j].x + v[j].y * v[j].y) + (v[j].z * v[j].z + v[j].w * v[j].w); }
;     const float rstd = 1.0f / sqrtf(wave_sum(s) * (1.f / DM) + EPS);
;     GAS unsigned long long* o8 = (GAS unsigned long long*)orow + lane;
; #pragma unroll
;     for (int j = 0; j < 8; ++j) { const f32x4 gg = gr[64 * j]; o8[64 * j] = (unsigned long long)pk2(v[j].x * rstd * gg.x, v[j].y * rstd * gg.y) | ((unsigned long long)pk2(v[j].z * rstd * gg.z, v[j].w * rstd * gg.w) << 32); }
; }
; __device__ __forceinline__ void p0_prologue(const Args& a, LAS unsigned char* lds, int wave, int lane, int G) {
;     ...
;     for (int m = gw; m < M + MMEM; m += NGW) {
;         if (m < M) rms_row_to_bf16(a.in[I_X] + (size_t)m * DM, a.in[I_GMIX], (bf16*)(ws + WS_XN) + (size_t)m * DM, lane);
.LBB0_110:
	s_andn2_b64 vcc, exec, s[0:1]
	s_cbranch_vccnz .LBB0_107
	global_load_dwordx4 v[62:65], v[58:59], off offset:-4096 nt
	global_load_dwordx4 v[26:29], v[58:59], off offset:-3072 nt
	global_load_dwordx4 v[22:25], v[58:59], off offset:-2048 nt
	global_load_dwordx4 v[18:21], v[58:59], off offset:-1024 nt
	global_load_dwordx4 v[14:17], v[58:59], off nt
	global_load_dwordx4 v[10:13], v[58:59], off offset:1024 nt
	global_load_dwordx4 v[6:9], v[58:59], off offset:2048 nt
	global_load_dwordx4 v[2:5], v[58:59], off offset:3072 nt
	global_load_dwordx4 v[66:69], v[46:47], off
	s_add_u32 s22, s16, 0x6900000
	s_addc_u32 s23, s17, 0
	s_waitcnt vmcnt(8)
	v_mul_f32_e32 v40, v63, v63
	v_mul_f32_e32 v41, v65, v65
	s_waitcnt vmcnt(7)
	v_mul_f32_e32 v70, v27, v27
	v_mul_f32_e32 v71, v29, v29
	s_waitcnt vmcnt(6)
	v_mul_f32_e32 v72, v23, v23
	v_mul_f32_e32 v73, v25, v25
	v_fmac_f32_e32 v40, v62, v62
	v_fmac_f32_e32 v41, v64, v64
	v_fmac_f32_e32 v70, v26, v26
	v_fmac_f32_e32 v71, v28, v28
	s_waitcnt vmcnt(5)
	v_mul_f32_e32 v74, v19, v19
	v_mul_f32_e32 v75, v21, v21
	v_fmac_f32_e32 v72, v22, v22
	v_fmac_f32_e32 v73, v24, v24
	v_add_f32_e32 v40, v40, v41
	v_add_f32_e32 v41, v70, v71
	s_waitcnt vmcnt(4)
	v_mul_f32_e32 v76, v15, v15
	v_mul_f32_e32 v77, v17, v17
	v_fmac_f32_e32 v74, v18, v18
	v_fmac_f32_e32 v75, v20, v20
	v_add_f32_e32 v70, v72, v73
	v_add_f32_e32 v40, v40, v41
	s_waitcnt vmcnt(3)
	v_mul_f32_e32 v78, v11, v11
	v_mul_f32_e32 v79, v13, v13
	v_fmac_f32_e32 v76, v14, v14
	v_fmac_f32_e32 v77, v16, v16
	v_add_f32_e32 v71, v74, v75
	v_add_f32_e32 v40, v40, v70
	s_waitcnt vmcnt(2)
	v_mul_f32_e32 v80, v7, v7
	v_mul_f32_e32 v81, v9, v9
	v_fmac_f32_e32 v78, v10, v10
	v_fmac_f32_e32 v79, v12, v12
	v_add_f32_e32 v72, v76, v77
	v_add_f32_e32 v40, v40, v71
	s_waitcnt vmcnt(1)
	global_load_dwordx4 v[96:99], v[46:47], off offset:1024
	global_load_dwordx4 v[100:103], v[46:47], off offset:2048
	global_load_dwordx4 v[104:107], v[46:47], off offset:3072
	global_load_dwordx4 v[108:111], v[48:49], off
	global_load_dwordx4 v[112:115], v[50:51], off
	global_load_dwordx4 v[116:119], v[52:53], off
	global_load_dwordx4 v[120:123], v[54:55], off
	v_mul_f32_e32 v82, v3, v3
	v_mul_f32_e32 v83, v5, v5
	v_fmac_f32_e32 v80, v6, v6
	v_fmac_f32_e32 v81, v8, v8
	v_add_f32_e32 v73, v78, v79
	v_add_f32_e32 v40, v40, v72
	v_fmac_f32_e32 v82, v2, v2
	v_fmac_f32_e32 v83, v4, v4
	v_add_f32_e32 v74, v80, v81
	v_add_f32_e32 v40, v40, v73
	v_add_f32_e32 v75, v82, v83
	v_add_f32_e32 v40, v40, v74
	v_add_f32_e32 v40, v40, v75
	s_nop 1
	v_mov_b32_dpp v41, v40 quad_perm:[1,0,3,2] row_mask:0xf bank_mask:0xf
	s_waitcnt lgkmcnt(0)
	v_add_f32_e32 v40, v40, v41
	s_nop 1
	v_mov_b32_dpp v41, v40 quad_perm:[2,3,0,1] row_mask:0xf bank_mask:0xf
	s_waitcnt lgkmcnt(0)
	v_add_f32_e32 v40, v40, v41
	s_nop 1
	v_mov_b32_dpp v41, v40 quad_perm:[3,2,1,0] row_mask:0xf bank_mask:0xf
	s_nop 1
	v_mov_b32_dpp v41, v41 row_half_mirror row_mask:0xf bank_mask:0xf
	s_waitcnt lgkmcnt(0)
	v_add_f32_e32 v40, v40, v41
	s_nop 1
	v_mov_b32_dpp v41, v40 row_half_mirror row_mask:0xf bank_mask:0xf
	s_nop 1
	v_mov_b32_dpp v41, v41 row_mirror row_mask:0xf bank_mask:0xf
	s_waitcnt lgkmcnt(0)
	v_add_f32_e32 v40, v40, v41
	ds_swizzle_b32 v41, v40 offset:swizzle(SWAP,16)
	s_waitcnt lgkmcnt(0)
	v_add_f32_e32 v40, v40, v41
	v_mov_b32_e32 v41, v40
	s_nop 1
	v_permlane32_swap_b32_e32 v40, v41
	v_add_f32_e32 v40, v40, v41
	v_fmamk_f32 v40, v40, 0x3a000000, v44
	v_mul_f32_e32 v41, 0x4f800000, v40
	v_cmp_gt_f32_e32 vcc, s7, v40
	s_nop 1
	v_cndmask_b32_e32 v70, v40, v41, vcc
	v_sqrt_f32_e32 v71, v70
	v_lshl_add_u64 v[40:41], s[16:17], 0, v[38:39]
	v_add_u32_e32 v72, -1, v71
	v_add_u32_e32 v73, 1, v71
	v_fma_f32 v74, -v72, v71, v70
	v_fma_f32 v75, -v73, v71, v70
	v_cmp_ge_f32_e64 s[0:1], 0, v74
	s_nop 1
	v_cndmask_b32_e64 v71, v71, v72, s[0:1]
	v_cmp_lt_f32_e64 s[0:1], 0, v75
	s_nop 1
	v_cndmask_b32_e64 v71, v71, v73, s[0:1]
	v_mul_f32_e32 v72, 0x37800000, v71
	v_cndmask_b32_e32 v71, v71, v72, vcc
	v_cmp_class_f32_e32 vcc, v70, v45
	s_nop 1
	v_cndmask_b32_e32 v72, v71, v70, vcc
	v_div_scale_f32 v73, s[0:1], v72, v72, 1.0
	v_rcp_f32_e32 v74, v73
	v_add_co_u32_e32 v70, vcc, s28, v40
	s_nop 1
	v_addc_co_u32_e32 v71, vcc, 0, v41, vcc
	v_fma_f32 v41, -v73, v74, 1.0
	v_div_scale_f32 v40, vcc, 1.0, v72, 1.0
	v_fmac_f32_e32 v74, v41, v74
	v_mul_f32_e32 v41, v40, v74
	v_fma_f32 v75, -v73, v41, v40
	v_fmac_f32_e32 v41, v75, v74
	v_fma_f32 v40, -v73, v41, v40
	v_div_fmas_f32 v40, v40, v74, v41
	v_div_fixup_f32 v40, v40, v72, 1.0
	v_mul_f32_e32 v41, v62, v40
	v_mul_f32_e32 v62, v63, v40
	v_mul_f32_e32 v63, v64, v40
	v_mul_f32_e32 v64, v65, v40
	s_waitcnt vmcnt(0)
; #define GAS __attribute__((address_space(1)))
; __device__ __forceinline__ unsigned pk2(float lo, float hi) { return f2bf(lo) | (f2bf(hi) << 16); }
; __device__ __forceinline__ float wave_sum(float v) { v += shx<1>(v); v += shx<2>(v); v += shx<4>(v); v += shx<8>(v); v += shx<16>(v); return sum32(v); }
; __device__ __forceinline__ void rms_row_to_bf16(const float* xrow, const float* g, bf16* orow, int lane) {
;     ...
;     const float rstd = 1.0f / sqrtf(wave_sum(s) * (1.f / DM) + EPS);
;     GAS unsigned long long* o8 = (GAS unsigned long long*)orow + lane;
; #pragma unroll
;     for (int j = 0; j < 8; ++j) { const f32x4 gg = gr[64 * j]; o8[64 * j] = (unsigned long long)pk2(v[j].x * rstd * gg.x, v[j].y * rstd * gg.y) | ((unsigned long long)pk2(v[j].z * rstd * gg.z, v[j].w * rstd * gg.w) << 32); }
	v_mul_f32_e32 v41, v66, v41
	v_mul_f32_e32 v63, v68, v63
	v_mul_f32_e32 v62, v67, v62
	v_mul_f32_e32 v64, v69, v64
	v_bfe_u32 v65, v41, 16, 1
	v_bfe_u32 v67, v63, 16, 1
	v_bfe_u32 v66, v62, 16, 1
	v_bfe_u32 v68, v64, 16, 1
	v_add3_u32 v41, v41, v65, s26
	v_add3_u32 v63, v63, v67, s26
	v_add3_u32 v62, v62, v66, s26
	v_add3_u32 v64, v64, v68, s26
	v_lshrrev_b32_e32 v41, 16, v41
	v_lshrrev_b32_e32 v63, 16, v63
	v_and_or_b32 v62, v62, s27, v41
	v_and_or_b32 v63, v64, s27, v63
	global_store_dwordx2 v[70:71], v[62:63], off
	v_mul_f32_e32 v26, v26, v40
	v_mul_f32_e32 v28, v28, v40
	v_mul_f32_e32 v27, v27, v40
	v_mul_f32_e32 v29, v29, v40
	v_mul_f32_e32 v22, v22, v40
	v_mul_f32_e32 v24, v24, v40
	v_mul_f32_e32 v23, v23, v40
	v_mul_f32_e32 v25, v25, v40
	v_mul_f32_e32 v18, v18, v40
	v_mul_f32_e32 v20, v20, v40
	v_mul_f32_e32 v19, v19, v40
	v_mul_f32_e32 v21, v21, v40
	v_mul_f32_e32 v14, v14, v40
	v_mul_f32_e32 v16, v16, v40
	v_mul_f32_e32 v15, v15, v40
	v_mul_f32_e32 v17, v17, v40
	v_mul_f32_e32 v10, v10, v40
	v_mul_f32_e32 v12, v12, v40
	v_mul_f32_e32 v11, v11, v40
	v_mul_f32_e32 v13, v13, v40
	v_mul_f32_e32 v6, v6, v40
	v_mul_f32_e32 v8, v8, v40
	v_mul_f32_e32 v7, v7, v40
	v_mul_f32_e32 v9, v9, v40
	v_mov_b32_e32 v62, v96
	v_mov_b32_e32 v63, v97
	v_mov_b32_e32 v64, v98
	v_mov_b32_e32 v65, v99
	v_mul_f32_e32 v26, v62, v26
	v_mul_f32_e32 v28, v64, v28
	v_mul_f32_e32 v27, v63, v27
	v_mul_f32_e32 v29, v65, v29
	v_bfe_u32 v41, v26, 16, 1
	v_bfe_u32 v63, v28, 16, 1
	v_bfe_u32 v62, v27, 16, 1
	v_bfe_u32 v64, v29, 16, 1
	v_add3_u32 v26, v26, v41, s26
	v_add3_u32 v28, v28, v63, s26
	v_add3_u32 v27, v27, v62, s26
	v_add3_u32 v29, v29, v64, s26
	v_lshrrev_b32_e32 v26, 16, v26
	v_lshrrev_b32_e32 v28, 16, v28
	v_and_or_b32 v26, v27, s27, v26
	v_and_or_b32 v27, v29, s27, v28
	global_store_dwordx2 v[70:71], v[26:27], off offset:512
	v_pk_mul_f32 v[2:3], v[2:3], v[40:41] op_sel_hi:[1,0]
	v_mul_f32_e32 v41, v4, v40
	v_mov_b32_e32 v26, v100
	v_mov_b32_e32 v27, v101
	v_mov_b32_e32 v28, v102
	v_mov_b32_e32 v29, v103
	v_mul_f32_e32 v22, v26, v22
	v_mul_f32_e32 v24, v28, v24
	v_mul_f32_e32 v23, v27, v23
	v_mul_f32_e32 v25, v29, v25
	v_bfe_u32 v26, v22, 16, 1
	v_bfe_u32 v28, v24, 16, 1
	v_bfe_u32 v27, v23, 16, 1
	v_bfe_u32 v29, v25, 16, 1
	v_add3_u32 v22, v22, v26, s26
	v_add3_u32 v24, v24, v28, s26
	v_add3_u32 v23, v23, v27, s26
	v_add3_u32 v25, v25, v29, s26
	v_lshrrev_b32_e32 v22, 16, v22
	v_lshrrev_b32_e32 v24, 16, v24
	v_and_or_b32 v22, v23, s27, v22
	v_and_or_b32 v23, v25, s27, v24
	global_store_dwordx2 v[70:71], v[22:23], off offset:1024
	v_mov_b32_e32 v22, v104
	v_mov_b32_e32 v23, v105
	v_mov_b32_e32 v24, v106
	v_mov_b32_e32 v25, v107
	v_mul_f32_e32 v18, v18, v22
	v_mul_f32_e32 v20, v20, v24
	v_mul_f32_e32 v19, v19, v23
	v_mul_f32_e32 v21, v21, v25
	v_bfe_u32 v22, v18, 16, 1
	v_bfe_u32 v24, v20, 16, 1
	v_bfe_u32 v23, v19, 16, 1
	v_bfe_u32 v25, v21, 16, 1
	v_add3_u32 v18, v18, v22, s26
	v_add3_u32 v20, v20, v24, s26
	v_add3_u32 v19, v19, v23, s26
	v_add3_u32 v21, v21, v25, s26
	v_lshrrev_b32_e32 v18, 16, v18
	v_lshrrev_b32_e32 v20, 16, v20
	v_and_or_b32 v18, v19, s27, v18
	v_and_or_b32 v19, v21, s27, v20
	global_store_dwordx2 v[70:71], v[18:19], off offset:1536
	v_mov_b32_e32 v18, v108
	v_mov_b32_e32 v19, v109
	v_mov_b32_e32 v20, v110
	v_mov_b32_e32 v21, v111
	v_mul_f32_e32 v14, v14, v18
	v_mul_f32_e32 v16, v16, v20
	v_mul_f32_e32 v15, v15, v19
	v_mul_f32_e32 v17, v17, v21
	v_bfe_u32 v18, v14, 16, 1
	v_bfe_u32 v20, v16, 16, 1
	v_bfe_u32 v19, v15, 16, 1
	v_bfe_u32 v21, v17, 16, 1
	v_add3_u32 v14, v14, v18, s26
	v_add3_u32 v16, v16, v20, s26
	v_add3_u32 v15, v15, v19, s26
	v_add3_u32 v17, v17, v21, s26
	v_lshrrev_b32_e32 v14, 16, v14
	v_lshrrev_b32_e32 v16, 16, v16
	v_and_or_b32 v14, v15, s27, v14
	v_and_or_b32 v15, v17, s27, v16
	global_store_dwordx2 v[70:71], v[14:15], off offset:2048
	v_mov_b32_e32 v14, v112
	v_mov_b32_e32 v15, v113
	v_mov_b32_e32 v16, v114
	v_mov_b32_e32 v17, v115
	v_mul_f32_e32 v10, v10, v14
	v_mul_f32_e32 v12, v12, v16
	v_mul_f32_e32 v11, v11, v15
	v_mul_f32_e32 v13, v13, v17
	v_bfe_u32 v14, v10, 16, 1
	v_bfe_u32 v16, v12, 16, 1
	v_bfe_u32 v15, v11, 16, 1
	v_bfe_u32 v17, v13, 16, 1
	v_add3_u32 v10, v10, v14, s26
	v_add3_u32 v12, v12, v16, s26
	v_add3_u32 v11, v11, v15, s26
	v_add3_u32 v13, v13, v17, s26
	v_lshrrev_b32_e32 v10, 16, v10
	v_lshrrev_b32_e32 v12, 16, v12
	v_and_or_b32 v10, v11, s27, v10
	v_and_or_b32 v11, v13, s27, v12
	global_store_dwordx2 v[70:71], v[10:11], off offset:2560
	v_mov_b32_e32 v10, v116
	v_mov_b32_e32 v11, v117
	v_mov_b32_e32 v12, v118
	v_mov_b32_e32 v13, v119
	v_mul_f32_e32 v6, v6, v10
	v_mul_f32_e32 v8, v8, v12
	v_mul_f32_e32 v7, v7, v11
	v_mul_f32_e32 v9, v9, v13
	v_bfe_u32 v10, v6, 16, 1
	v_bfe_u32 v12, v8, 16, 1
	v_bfe_u32 v11, v7, 16, 1
	v_bfe_u32 v13, v9, 16, 1
	v_add3_u32 v6, v6, v10, s26
	v_add3_u32 v8, v8, v12, s26
	v_add3_u32 v7, v7, v11, s26
	v_add3_u32 v9, v9, v13, s26
	v_lshrrev_b32_e32 v6, 16, v6
	v_lshrrev_b32_e32 v8, 16, v8
	v_and_or_b32 v6, v7, s27, v6
	v_and_or_b32 v7, v9, s27, v8
	global_store_dwordx2 v[70:71], v[6:7], off offset:3072
	v_mov_b32_e32 v6, v120
	v_mov_b32_e32 v7, v121
	v_mov_b32_e32 v8, v122
	v_mov_b32_e32 v9, v123
	v_pk_mul_f32 v[2:3], v[2:3], v[6:7]
	s_nop 0
	v_and_b32_sdwa v7, v2, v61 dst_sel:DWORD dst_unused:UNUSED_PAD src0_sel:WORD_1 src1_sel:DWORD
	v_and_b32_sdwa v6, v3, v61 dst_sel:DWORD dst_unused:UNUSED_PAD src0_sel:WORD_1 src1_sel:DWORD
	v_add3_u32 v2, v2, v7, s26
	v_pk_mov_b32 v[4:5], v[4:5], v[8:9] op_sel:[1,0]
	v_add3_u32 v3, v3, v6, s26
	v_lshrrev_b32_e32 v2, 16, v2
	v_and_or_b32 v2, v3, s27, v2
	v_pk_mul_f32 v[4:5], v[4:5], v[40:41]
	s_branch .LBB0_107
